# v3: + GLA-B state rebuild loads batched (1 round trip per segment step), phase-4 gate-weight loads issued before first use
# speedup vs baseline: 1.0115x; 1.0010x over previous
.LBB0_103:
	s_ashr_i32 s43, s42, 31
	s_ashr_i32 s45, s44, 31
	s_lshl_b64 s[62:63], s[42:43], 14
	v_lshl_add_u64 v[8:9], s[44:45], 2, v[4:5]
	v_lshl_add_u64 v[6:7], v[2:3], 0, s[62:63]
	global_load_dwordx4 v[84:87], v[8:9], off
	global_load_dwordx4 v[88:91], v[8:9], off offset:32
	global_load_dwordx4 v[92:95], v[8:9], off offset:64
	global_load_dwordx4 v[96:99], v[8:9], off offset:96
	global_load_dwordx4 v[100:103], v[8:9], off offset:128
	global_load_dwordx4 v[104:107], v[8:9], off offset:160
	global_load_dwordx4 v[108:111], v[8:9], off offset:192
	global_load_dwordx4 v[112:115], v[8:9], off offset:224
	global_load_dwordx4 v[116:119], v[8:9], off offset:256
	global_load_dwordx4 v[120:123], v[8:9], off offset:288
	global_load_dwordx4 v[124:127], v[8:9], off offset:320
	global_load_dwordx4 v[128:131], v[8:9], off offset:352
	global_load_dwordx4 v[132:135], v[8:9], off offset:384
	global_load_dwordx4 v[136:139], v[8:9], off offset:416
	global_load_dwordx4 v[140:143], v[8:9], off offset:448
	global_load_dwordx4 v[144:147], v[8:9], off offset:480
	global_load_dwordx4 v[152:155], v[6:7], off
	global_load_dwordx4 v[156:159], v[6:7], off offset:16
	global_load_dwordx4 v[160:163], v[6:7], off offset:32
	global_load_dwordx4 v[168:171], v[6:7], off offset:48
	global_load_dwordx4 v[172:175], v[6:7], off offset:64
	global_load_dwordx4 v[176:179], v[6:7], off offset:80
	global_load_dwordx4 v[180:183], v[6:7], off offset:96
	global_load_dwordx4 v[184:187], v[6:7], off offset:112
	global_load_dwordx4 v[188:191], v[6:7], off offset:128
	global_load_dwordx4 v[192:195], v[6:7], off offset:144
	global_load_dwordx4 v[196:199], v[6:7], off offset:160
	global_load_dwordx4 v[200:203], v[6:7], off offset:176
	global_load_dwordx4 v[210:213], v[6:7], off offset:192
	global_load_dwordx4 v[214:217], v[6:7], off offset:208
	global_load_dwordx4 v[228:231], v[6:7], off offset:224
	global_load_dwordx4 v[232:235], v[6:7], off offset:240
	s_add_i32 s55, s55, -1
	s_add_i32 s42, s42, 8
	s_addk_i32 s44, 0x80
	s_cmp_eq_u32 s55, 0
	s_waitcnt vmcnt(15)
	v_pk_fma_f32 v[64:65], v[84:85], v[64:65], v[152:153]
	v_pk_fma_f32 v[66:67], v[86:87], v[66:67], v[154:155]
	s_waitcnt vmcnt(14)
	v_pk_fma_f32 v[68:69], v[88:89], v[68:69], v[156:157]
	v_pk_fma_f32 v[70:71], v[90:91], v[70:71], v[158:159]
	s_waitcnt vmcnt(13)
	v_pk_fma_f32 v[72:73], v[92:93], v[72:73], v[160:161]
	v_pk_fma_f32 v[74:75], v[94:95], v[74:75], v[162:163]
	s_waitcnt vmcnt(12)
	v_pk_fma_f32 v[76:77], v[96:97], v[76:77], v[168:169]
	v_pk_fma_f32 v[78:79], v[98:99], v[78:79], v[170:171]
	s_waitcnt vmcnt(11)
	v_pk_fma_f32 v[48:49], v[100:101], v[48:49], v[172:173]
	v_pk_fma_f32 v[50:51], v[102:103], v[50:51], v[174:175]
	s_waitcnt vmcnt(10)
	v_pk_fma_f32 v[52:53], v[104:105], v[52:53], v[176:177]
	v_pk_fma_f32 v[54:55], v[106:107], v[54:55], v[178:179]
	s_waitcnt vmcnt(9)
	v_pk_fma_f32 v[56:57], v[108:109], v[56:57], v[180:181]
	v_pk_fma_f32 v[58:59], v[110:111], v[58:59], v[182:183]
	s_waitcnt vmcnt(8)
	v_pk_fma_f32 v[60:61], v[112:113], v[60:61], v[184:185]
	v_pk_fma_f32 v[62:63], v[114:115], v[62:63], v[186:187]
	s_waitcnt vmcnt(7)
	v_pk_fma_f32 v[32:33], v[116:117], v[32:33], v[188:189]
	v_pk_fma_f32 v[34:35], v[118:119], v[34:35], v[190:191]
	s_waitcnt vmcnt(6)
	v_pk_fma_f32 v[36:37], v[120:121], v[36:37], v[192:193]
	v_pk_fma_f32 v[38:39], v[122:123], v[38:39], v[194:195]
	s_waitcnt vmcnt(5)
	v_pk_fma_f32 v[40:41], v[124:125], v[40:41], v[196:197]
	v_pk_fma_f32 v[42:43], v[126:127], v[42:43], v[198:199]
	s_waitcnt vmcnt(4)
	v_pk_fma_f32 v[44:45], v[128:129], v[44:45], v[200:201]
	v_pk_fma_f32 v[46:47], v[130:131], v[46:47], v[202:203]
	s_waitcnt vmcnt(3)
	v_pk_fma_f32 v[16:17], v[132:133], v[16:17], v[210:211]
	v_pk_fma_f32 v[18:19], v[134:135], v[18:19], v[212:213]
	s_waitcnt vmcnt(2)
	v_pk_fma_f32 v[20:21], v[136:137], v[20:21], v[214:215]
	v_pk_fma_f32 v[22:23], v[138:139], v[22:23], v[216:217]
	s_waitcnt vmcnt(1)
	v_pk_fma_f32 v[24:25], v[140:141], v[24:25], v[228:229]
	v_pk_fma_f32 v[26:27], v[142:143], v[26:27], v[230:231]
	s_waitcnt vmcnt(0)
	v_pk_fma_f32 v[28:29], v[144:145], v[28:29], v[232:233]
	v_pk_fma_f32 v[30:31], v[146:147], v[30:31], v[234:235]
	s_cbranch_scc0 .LBB0_103
	s_branch .LBB0_106

.LBB0_182:
	v_lshl_add_u64 v[66:67], v[74:75], 0, s[40:41]
	v_add_co_u32_e32 v68, vcc, 0x1000, v66
	global_load_dword v146, v[66:67], off
	global_load_dword v148, v[66:67], off offset:2048
	v_addc_co_u32_e32 v69, vcc, 0, v67, vcc
	global_load_dword v150, v[68:69], off
	global_load_dword v144, v[68:69], off offset:2048
	v_add_co_u32_e32 v68, vcc, 0x2000, v66
	s_nop 1
	v_addc_co_u32_e32 v69, vcc, 0, v67, vcc
	global_load_dword v147, v[68:69], off
	global_load_dword v149, v[68:69], off offset:2048
	v_add_co_u32_e32 v68, vcc, 0x3000, v66
	s_nop 1
	v_addc_co_u32_e32 v69, vcc, 0, v67, vcc
	global_load_dword v151, v[68:69], off
	global_load_dword v145, v[68:69], off offset:2048
	v_add_co_u32_e32 v68, vcc, 0x4000, v66
	s_nop 1
	v_addc_co_u32_e32 v69, vcc, 0, v67, vcc
	global_load_dword v154, v[68:69], off
	global_load_dword v156, v[68:69], off offset:2048
	v_add_co_u32_e32 v68, vcc, 0x5000, v66
	s_nop 1
	v_addc_co_u32_e32 v69, vcc, 0, v67, vcc
	global_load_dword v158, v[68:69], off
	global_load_dword v152, v[68:69], off offset:2048
	v_add_co_u32_e32 v68, vcc, 0x6000, v66
	s_nop 1
	v_addc_co_u32_e32 v69, vcc, 0, v67, vcc
	v_add_co_u32_e32 v66, vcc, 0x7000, v66
	global_load_dword v155, v[68:69], off
	global_load_dword v157, v[68:69], off offset:2048
	v_addc_co_u32_e32 v67, vcc, 0, v67, vcc
	global_load_dword v159, v[66:67], off
	global_load_dword v153, v[66:67], off offset:2048
	v_lshl_add_u64 v[66:67], v[72:73], 0, s[40:41]
	global_load_dword v141, v[66:67], off
	s_nop 0
	global_load_dwordx4 v[66:69], v[142:143], off
	s_waitcnt vmcnt(12)
	v_pk_mul_f32 v[160:161], v[54:55], v[148:149]
	v_pk_mul_f32 v[166:167], v[62:63], v[148:149]
	v_pk_fma_f32 v[160:161], v[136:137], v[146:147], v[160:161]
	v_pk_fma_f32 v[166:167], v[128:129], v[146:147], v[166:167]
	v_pk_mul_f32 v[172:173], v[46:47], v[148:149]
	v_pk_mul_f32 v[174:175], v[30:31], v[148:149]
	v_pk_fma_f32 v[172:173], v[120:121], v[146:147], v[172:173]
	v_pk_fma_f32 v[174:175], v[104:105], v[146:147], v[174:175]
	s_waitcnt vmcnt(11)
	v_pk_fma_f32 v[160:161], v[138:139], v[150:151], v[160:161]
	s_waitcnt vmcnt(10)
	v_pk_fma_f32 v[160:161], v[56:57], v[144:145], v[160:161]
	v_pk_fma_f32 v[166:167], v[130:131], v[150:151], v[166:167]
	v_pk_fma_f32 v[172:173], v[122:123], v[150:151], v[172:173]
	v_pk_fma_f32 v[166:167], v[64:65], v[144:145], v[166:167]
	v_pk_fma_f32 v[172:173], v[48:49], v[144:145], v[172:173]
	v_pk_fma_f32 v[174:175], v[106:107], v[150:151], v[174:175]
	s_waitcnt vmcnt(1)
	v_add_f32_e32 v160, v141, v160
	v_add_f32_e32 v162, v160, v161
	v_pk_mul_f32 v[160:161], v[58:59], v[156:157]
	v_pk_fma_f32 v[174:175], v[32:33], v[144:145], v[174:175]
	v_pk_fma_f32 v[160:161], v[132:133], v[154:155], v[160:161]
	s_nop 0
	v_pk_fma_f32 v[160:161], v[134:135], v[158:159], v[160:161]
	s_nop 0
	v_pk_fma_f32 v[160:161], v[60:61], v[152:153], v[160:161]
	s_nop 0
	v_add_f32_e32 v160, v162, v160
	v_add_f32_e32 v161, v160, v161
	v_min_f32_e32 v160, 0, v161
	v_mul_f32_e64 v161, |v161|, s87
	v_exp_f32_e32 v161, v161
	s_nop 0
	v_add_f32_e32 v161, 1.0, v161
	v_cmp_gt_f32_e32 vcc, s88, v161
	s_nop 1
	v_cndmask_b32_e64 v162, 0, 32, vcc
	v_ldexp_f32 v161, v161, v162
	v_log_f32_e32 v161, v161
	s_nop 0
	v_mul_f32_e32 v162, 0x3f317217, v161
	v_fma_f32 v162, v161, s89, -v162
	v_fmac_f32_e32 v162, 0x3377d1cf, v161
	v_fmac_f32_e32 v162, 0x3f317217, v161
	v_cmp_lt_f32_e64 s[52:53], |v161|, s90
	s_nop 1
	v_cndmask_b32_e64 v161, v161, v162, s[52:53]
	v_cndmask_b32_e32 v162, 0, v209, vcc
	v_sub_f32_e32 v162, v161, v162
	v_add_f32_e32 v161, v141, v166
	v_add_f32_e32 v161, v161, v167
	v_pk_mul_f32 v[166:167], v[50:51], v[156:157]
	s_nop 0
	v_pk_fma_f32 v[166:167], v[124:125], v[154:155], v[166:167]
	s_nop 0
	v_pk_fma_f32 v[166:167], v[126:127], v[158:159], v[166:167]
	s_nop 0
	v_pk_fma_f32 v[166:167], v[52:53], v[152:153], v[166:167]
	s_nop 0
	v_add_f32_e32 v161, v161, v166
	v_add_f32_e32 v163, v161, v167
	v_min_f32_e32 v161, 0, v163
	v_mul_f32_e64 v163, |v163|, s87
	v_exp_f32_e32 v163, v163
	s_nop 0
	v_add_f32_e32 v163, 1.0, v163
	v_cmp_gt_f32_e32 vcc, s88, v163
	s_nop 1
	v_cndmask_b32_e64 v166, 0, 32, vcc
	v_ldexp_f32 v163, v163, v166
	v_log_f32_e32 v163, v163
	s_nop 0
	v_mul_f32_e32 v166, 0x3f317217, v163
	v_fma_f32 v166, v163, s89, -v166
	v_fmac_f32_e32 v166, 0x3377d1cf, v163
	v_fmac_f32_e32 v166, 0x3f317217, v163
	v_cmp_lt_f32_e64 s[52:53], |v163|, s90
	s_nop 1
	v_cndmask_b32_e64 v163, v163, v166, s[52:53]
	v_cndmask_b32_e32 v166, 0, v209, vcc
	v_sub_f32_e32 v163, v163, v166
	v_pk_add_f32 v[160:161], v[160:161], v[162:163] neg_lo:[0,1] neg_hi:[0,1]
	s_nop 0
	v_pk_mul_f32 v[160:161], v[160:161], s[16:17] op_sel_hi:[1,0]
	s_nop 0
	v_add_f32_e32 v162, 0, v160
	v_add_f32_e32 v171, v162, v161
	v_pk_mul_f32 v[162:163], v[42:43], v[148:149]
	s_nop 0
	v_pk_fma_f32 v[162:163], v[116:117], v[146:147], v[162:163]
	s_nop 0
	v_pk_fma_f32 v[162:163], v[118:119], v[150:151], v[162:163]
	s_nop 0
	v_pk_fma_f32 v[162:163], v[44:45], v[144:145], v[162:163]
	s_nop 0
	v_add_f32_e32 v162, v141, v162
	v_add_f32_e32 v166, v162, v163
	v_pk_mul_f32 v[162:163], v[34:35], v[156:157]
	s_nop 0
	v_pk_fma_f32 v[162:163], v[108:109], v[154:155], v[162:163]
	s_nop 0
	v_pk_fma_f32 v[162:163], v[110:111], v[158:159], v[162:163]
	s_nop 0
	v_pk_fma_f32 v[162:163], v[36:37], v[152:153], v[162:163]
	s_nop 0
	v_add_f32_e32 v162, v166, v162
	v_add_f32_e32 v163, v162, v163
	v_min_f32_e32 v162, 0, v163
	v_mul_f32_e64 v163, |v163|, s87
	v_exp_f32_e32 v163, v163
	s_nop 0
	v_add_f32_e32 v163, 1.0, v163
	v_cmp_gt_f32_e32 vcc, s88, v163
	s_nop 1
	v_cndmask_b32_e64 v166, 0, 32, vcc
	v_ldexp_f32 v163, v163, v166
	v_log_f32_e32 v163, v163
	s_nop 0
	v_mul_f32_e32 v166, 0x3f317217, v163
	v_fma_f32 v166, v163, s89, -v166
	v_fmac_f32_e32 v166, 0x3377d1cf, v163
	v_fmac_f32_e32 v166, 0x3f317217, v163
	v_cmp_lt_f32_e64 s[52:53], |v163|, s90
	s_nop 1
	v_cndmask_b32_e64 v163, v163, v166, s[52:53]
	v_cndmask_b32_e32 v166, 0, v209, vcc
	v_sub_f32_e32 v166, v163, v166
	v_add_f32_e32 v163, v141, v172
	v_add_f32_e32 v163, v163, v173
	v_pk_mul_f32 v[172:173], v[38:39], v[156:157]
	s_nop 0
	v_pk_fma_f32 v[172:173], v[112:113], v[154:155], v[172:173]
	s_nop 0
	v_pk_fma_f32 v[172:173], v[114:115], v[158:159], v[172:173]
	s_nop 0
	v_pk_fma_f32 v[172:173], v[40:41], v[152:153], v[172:173]
	s_nop 0
	v_add_f32_e32 v163, v163, v172
	v_add_f32_e32 v167, v163, v173
	v_min_f32_e32 v163, 0, v167
	v_mul_f32_e64 v167, |v167|, s87
	v_exp_f32_e32 v167, v167
	s_nop 0
	v_add_f32_e32 v167, 1.0, v167
	v_cmp_gt_f32_e32 vcc, s88, v167
	s_nop 1
	v_cndmask_b32_e64 v172, 0, 32, vcc
	v_ldexp_f32 v167, v167, v172
	v_log_f32_e32 v167, v167
	s_nop 0
	v_mul_f32_e32 v172, 0x3f317217, v167
	v_fma_f32 v172, v167, s89, -v172
	v_fmac_f32_e32 v172, 0x3377d1cf, v167
	v_fmac_f32_e32 v172, 0x3f317217, v167
	v_cmp_lt_f32_e64 s[52:53], |v167|, s90
	s_nop 1
	v_cndmask_b32_e64 v167, v167, v172, s[52:53]
	v_cndmask_b32_e32 v172, 0, v209, vcc
	v_sub_f32_e32 v167, v167, v172
	v_pk_add_f32 v[162:163], v[162:163], v[166:167] neg_lo:[0,1] neg_hi:[0,1]
	s_nop 0
	v_pk_mul_f32 v[162:163], v[162:163], s[16:17] op_sel_hi:[1,0]
	s_nop 0
	v_add_f32_e32 v166, v171, v162
	v_add_f32_e32 v171, v166, v163
	v_pk_mul_f32 v[166:167], v[26:27], v[148:149]
	s_nop 0
	v_pk_fma_f32 v[166:167], v[100:101], v[146:147], v[166:167]
	s_nop 0
	v_pk_fma_f32 v[166:167], v[102:103], v[150:151], v[166:167]
	s_nop 0
	v_pk_fma_f32 v[166:167], v[28:29], v[144:145], v[166:167]
	s_nop 0
	v_add_f32_e32 v166, v141, v166
	v_add_f32_e32 v172, v166, v167
	v_pk_mul_f32 v[166:167], v[22:23], v[156:157]
	s_nop 0
	v_pk_fma_f32 v[166:167], v[96:97], v[154:155], v[166:167]
	s_nop 0
	v_pk_fma_f32 v[166:167], v[98:99], v[158:159], v[166:167]
	s_nop 0
	v_pk_fma_f32 v[166:167], v[24:25], v[152:153], v[166:167]
	s_nop 0
	v_add_f32_e32 v166, v172, v166
	v_add_f32_e32 v167, v166, v167
	v_min_f32_e32 v166, 0, v167
	v_mul_f32_e64 v167, |v167|, s87
	v_exp_f32_e32 v167, v167
	s_nop 0
	v_add_f32_e32 v167, 1.0, v167
	v_cmp_gt_f32_e32 vcc, s88, v167
	s_nop 1
	v_cndmask_b32_e64 v172, 0, 32, vcc
	v_ldexp_f32 v167, v167, v172
	v_log_f32_e32 v167, v167
	s_nop 0
	v_mul_f32_e32 v172, 0x3f317217, v167
	v_fma_f32 v172, v167, s89, -v172
	v_fmac_f32_e32 v172, 0x3377d1cf, v167
	v_fmac_f32_e32 v172, 0x3f317217, v167
	v_cmp_lt_f32_e64 s[52:53], |v167|, s90
	s_nop 1
	v_cndmask_b32_e64 v167, v167, v172, s[52:53]
	v_cndmask_b32_e32 v172, 0, v209, vcc
	v_sub_f32_e32 v172, v167, v172
	v_add_f32_e32 v167, v141, v174
	v_add_f32_e32 v167, v167, v175
	v_pk_mul_f32 v[174:175], v[10:11], v[156:157]
	s_nop 0
	v_pk_fma_f32 v[174:175], v[84:85], v[154:155], v[174:175]
	s_nop 0
	v_pk_fma_f32 v[174:175], v[86:87], v[158:159], v[174:175]
	s_nop 0
	v_pk_fma_f32 v[174:175], v[12:13], v[152:153], v[174:175]
	s_nop 0
	v_add_f32_e32 v167, v167, v174
	v_add_f32_e32 v173, v167, v175
	v_min_f32_e32 v167, 0, v173
	v_mul_f32_e64 v173, |v173|, s87
	v_exp_f32_e32 v173, v173
	s_nop 0
	v_add_f32_e32 v173, 1.0, v173
	v_cmp_gt_f32_e32 vcc, s88, v173
	s_nop 1
	v_cndmask_b32_e64 v174, 0, 32, vcc
	v_ldexp_f32 v173, v173, v174
	v_log_f32_e32 v173, v173
	s_nop 0
	v_mul_f32_e32 v174, 0x3f317217, v173
	v_fma_f32 v174, v173, s89, -v174
	v_fmac_f32_e32 v174, 0x3377d1cf, v173
	v_fmac_f32_e32 v174, 0x3f317217, v173
	v_cmp_lt_f32_e64 s[52:53], |v173|, s90
	s_nop 1
	v_cndmask_b32_e64 v173, v173, v174, s[52:53]
	v_cndmask_b32_e32 v174, 0, v209, vcc
	v_sub_f32_e32 v173, v173, v174
	v_pk_add_f32 v[166:167], v[166:167], v[172:173] neg_lo:[0,1] neg_hi:[0,1]
	v_pk_mul_f32 v[172:173], v[18:19], v[148:149]
	v_pk_mul_f32 v[148:149], v[14:15], v[148:149]
	v_pk_fma_f32 v[172:173], v[92:93], v[146:147], v[172:173]
	v_pk_fma_f32 v[146:147], v[88:89], v[146:147], v[148:149]
	v_pk_fma_f32 v[172:173], v[94:95], v[150:151], v[172:173]
	v_pk_fma_f32 v[146:147], v[90:91], v[150:151], v[146:147]
	v_pk_fma_f32 v[172:173], v[20:21], v[144:145], v[172:173]
	v_pk_fma_f32 v[144:145], v[16:17], v[144:145], v[146:147]
	v_add_f32_e32 v172, v141, v172
	v_add_f32_e32 v174, v172, v173
	v_pk_mul_f32 v[172:173], v[6:7], v[156:157]
	v_add_f32_e32 v141, v141, v144
	v_pk_fma_f32 v[172:173], v[80:81], v[154:155], v[172:173]
	v_add_f32_e32 v141, v141, v145
	v_pk_fma_f32 v[172:173], v[82:83], v[158:159], v[172:173]
	v_pk_mul_f32 v[144:145], v[2:3], v[156:157]
	v_pk_fma_f32 v[172:173], v[8:9], v[152:153], v[172:173]
	v_pk_fma_f32 v[144:145], v[76:77], v[154:155], v[144:145]
	v_add_f32_e32 v172, v174, v172
	v_add_f32_e32 v173, v172, v173
	v_min_f32_e32 v172, 0, v173
	v_mul_f32_e64 v173, |v173|, s87
	v_exp_f32_e32 v173, v173
	v_pk_fma_f32 v[144:145], v[78:79], v[158:159], v[144:145]
	v_pk_mul_f32 v[166:167], v[166:167], s[16:17] op_sel_hi:[1,0]
	v_pk_fma_f32 v[144:145], v[4:5], v[152:153], v[144:145]
	v_add_f32_e32 v173, 1.0, v173
	v_cmp_gt_f32_e32 vcc, s88, v173
	v_add_f32_e32 v141, v141, v144
	v_add_f32_e32 v141, v141, v145
	v_cndmask_b32_e64 v174, 0, 32, vcc
	v_ldexp_f32 v173, v173, v174
	v_log_f32_e32 v173, v173
	v_add_f32_e32 v171, v171, v166
	v_add_f32_e32 v171, v171, v167
	s_waitcnt vmcnt(0)
	v_lshlrev_b32_e32 v148, 16, v69
	v_mul_f32_e32 v174, 0x3f317217, v173
	v_fma_f32 v174, v173, s89, -v174
	v_fmac_f32_e32 v174, 0x3377d1cf, v173
	v_fmac_f32_e32 v174, 0x3f317217, v173
	v_cmp_lt_f32_e64 s[52:53], |v173|, s90
	v_and_b32_e32 v149, 0xffff0000, v69
	v_lshlrev_b32_e32 v150, 16, v66
	v_cndmask_b32_e64 v173, v173, v174, s[52:53]
	v_cndmask_b32_e32 v174, 0, v209, vcc
	v_sub_f32_e32 v174, v173, v174
	v_min_f32_e32 v173, 0, v141
	v_mul_f32_e64 v141, |v141|, s87
	v_exp_f32_e32 v141, v141
	v_and_b32_e32 v151, 0xffff0000, v66
	v_add_f32_e32 v141, 1.0, v141
	v_cmp_gt_f32_e32 vcc, s88, v141
	s_nop 1
	v_cndmask_b32_e64 v144, 0, 32, vcc
	v_ldexp_f32 v141, v141, v144
	v_log_f32_e32 v141, v141
	s_nop 0
	v_mul_f32_e32 v144, 0x3f317217, v141
	v_fma_f32 v144, v141, s89, -v144
	v_fmac_f32_e32 v144, 0x3377d1cf, v141
	v_fmac_f32_e32 v144, 0x3f317217, v141
	v_cmp_lt_f32_e64 s[52:53], |v141|, s90
	s_nop 1
	v_cndmask_b32_e64 v141, v141, v144, s[52:53]
	v_cndmask_b32_e32 v144, 0, v209, vcc
	v_sub_f32_e32 v175, v141, v144
	v_pk_add_f32 v[144:145], v[172:173], v[174:175] neg_lo:[0,1] neg_hi:[0,1]
	s_nop 0
	v_pk_mul_f32 v[144:145], v[144:145], s[16:17] op_sel_hi:[1,0]
	s_nop 0
	v_add_f32_e32 v141, v171, v144
	v_add_f32_e32 v141, v141, v145
	ds_bpermute_b32 v146, v165, v141
	s_waitcnt lgkmcnt(0)
	v_add_f32_e32 v146, v141, v146
	v_cndmask_b32_e64 v146, v146, v141, s[42:43]
	ds_bpermute_b32 v147, v168, v146
	s_waitcnt lgkmcnt(0)
	v_add_f32_e32 v147, v146, v147
	v_cndmask_b32_e64 v146, v146, v147, s[44:45]
	ds_bpermute_b32 v147, v169, v146
	s_waitcnt lgkmcnt(0)
	v_add_f32_e32 v147, v146, v147
	v_cndmask_b32_e64 v146, v146, v147, s[46:47]
	v_sub_f32_e32 v141, v146, v141
	v_mul_f32_e32 v146, 0x3fb8aa3b, v141
	v_add_f32_e32 v141, v141, v145
	v_add_f32_e32 v69, v141, v144
	v_mul_f32_e32 v145, 0x3fb8aa3b, v141
	v_mul_f32_e32 v141, 0x3fb8aa3b, v69
	v_exp_f32_e32 v147, v146
	v_exp_f32_e32 v146, v145
	v_exp_f32_e32 v145, v141
	v_add_f32_e32 v141, v69, v167
	v_mul_f32_e32 v69, 0x3fb8aa3b, v141
	v_exp_f32_e32 v144, v69
	v_pk_mul_f32 v[148:149], v[146:147], v[148:149]
	v_lshlrev_b32_e32 v146, 16, v68
	v_and_b32_e32 v147, 0xffff0000, v68
	v_add_f32_e32 v141, v141, v166
	v_pk_mul_f32 v[68:69], v[144:145], v[146:147]
	v_mul_f32_e32 v144, 0x3fb8aa3b, v141
	v_add_f32_e32 v141, v141, v163
	v_exp_f32_e32 v145, v144
	v_mul_f32_e32 v144, 0x3fb8aa3b, v141
	v_exp_f32_e32 v144, v144
	v_lshlrev_b32_e32 v146, 16, v67
	v_and_b32_e32 v147, 0xffff0000, v67
	v_add_f32_e32 v67, v141, v162
	v_mul_f32_e32 v141, 0x3fb8aa3b, v67
	v_add_f32_e32 v67, v67, v161
	v_pk_mul_f32 v[146:147], v[144:145], v[146:147]
	v_exp_f32_e32 v145, v141
	v_mul_f32_e32 v141, 0x3fb8aa3b, v67
	v_exp_f32_e32 v144, v141
	s_nop 0
	v_pk_mul_f32 v[144:145], v[144:145], v[150:151]
	s_nop 0
	v_cvt_pk_bf16_f32 v144, v144, v145
	v_cvt_pk_bf16_f32 v145, v146, v147
	v_cvt_pk_bf16_f32 v146, v68, v69
	v_cvt_pk_bf16_f32 v147, v148, v149
	global_store_dwordx4 v[142:143], v[144:147], off
	s_and_saveexec_b64 s[50:51], s[48:49]
	s_cbranch_execz .LBB0_181
	v_add_f32_e32 v66, v67, v160
	v_mul_f32_e32 v66, 0x3fb8aa3b, v66
	v_exp_f32_e32 v68, v66
	v_ashrrev_i32_e32 v141, 31, v140
	v_lshl_add_u64 v[66:67], v[140:141], 2, s[22:23]
	global_store_dword v[66:67], v68, off
	s_branch .LBB0_181
